# Res unit order reversed within each workgroup (same XCD) + plain mid stores + conv4/scan group-major reverse order
# speedup vs baseline: 1.0104x; 1.0007x over previous
;     __host__ __device__ bool next(int i, Unit& u) const {
;         const long L = (long)i * G + c; if (L >= nwg) return false;
;         int wgid = (int)L; { const int q = nwg / NXCD, r = nwg % NXCD, xcd = wgid % NXCD, off = wgid / NXCD; wgid = (xcd < r ? xcd * (q + 1) : r * (q + 1) + (xcd - r) * q) + off; }
;         const int nig = WGM * nN, gid = wgid / nig, fm = gid * WGM, gsz = (nM - fm) < WGM ? (nM - fm) : WGM;
;         u.pm = fm + ((wgid % nig) % gsz); u.pn = (wgid % nig) / gsz; return true;
.LBB0_661:
	s_lshr_b32 s1, s17, 6
	v_mbcnt_lo_u32_b32 v0, -1, 0
	v_mbcnt_hi_u32_b32 v0, -1, v0
	s_cmpk_lt_i32 s85, 0x400
	s_waitcnt vmcnt(0)
	v_add_u32_e32 v18, s3, v0
	s_cselect_b64 s[28:29], -1, 0
	v_readfirstlane_b32 s22, v18
	s_cmpk_gt_i32 s85, 0x3ff
	s_cbranch_scc1 .LBB0_667
	s_add_i32 s23, s85, 0x300
	s_ashr_i32 s2, s23, 31
	s_lshr_b32 s2, s2, 29
	s_add_i32 s2, s23, s2
	s_and_b32 s4, s2, -8
	s_sub_i32 s4, s23, s4
	s_cmp_gt_i32 s4, -1
	s_mov_b64 s[36:37], -1
	s_cbranch_scc0 .LBB0_664
	s_lshl_b32 s18, s4, 7
	s_mov_b64 s[36:37], 0

;     __host__ __device__ bool next(int i, Unit& u) const {
;         const long L = (long)i * G + c; if (L >= nwg) return false;
;         int wgid = (int)L; { const int q = nwg / NXCD, r = nwg % NXCD, xcd = wgid % NXCD, off = wgid / NXCD; wgid = (xcd < r ? xcd * (q + 1) : r * (q + 1) + (xcd - r) * q) + off; }
;         const int nig = WGM * nN, gid = wgid / nig, fm = gid * WGM, gsz = (nM - fm) < WGM ? (nM - fm) : WGM;
;         u.pm = fm + ((wgid % nig) % gsz); u.pn = (wgid % nig) / gsz; return true;
; template <class Epi>
; __device__ __forceinline__ void gemm_phase(LAS unsigned char* lds, const Gemm g, const StaticOrder& S, const Epi& E, int tid_) {
;     ...
;         const bool has_next = S.next(ui + 1, nxt);
.LBB0_673:
	s_add_i32 s62, s62, 1
	s_mul_i32 s22, s62, s65
	s_mul_hi_u32 s23, s62, s0
	s_add_i32 s23, s23, s22
	s_mul_i32 s22, s62, s0
	s_add_u32 s38, s22, s85
	s_addc_u32 s39, s23, s66
	v_cmp_gt_i64_e32 vcc, s[38:39], v[196:197]
	v_cmp_lt_i64_e64 s[40:41], s[38:39], v[194:195]
	s_cbranch_vccnz .LBB0_679
	s_lshl_b32 s22, s85, 1
	s_add_i32 s22, s22, 0x300
	s_sub_i32 s38, s22, s38
	s_ashr_i32 s22, s38, 31
	s_lshr_b32 s22, s22, 29
	s_add_i32 s22, s38, s22
	s_and_b32 s23, s22, -8
	s_sub_i32 s23, s38, s23
	s_cmp_gt_i32 s23, -1
	s_mov_b64 s[38:39], -1
	s_cbranch_scc0 .LBB0_676
	s_lshl_b32 s52, s23, 7
	s_mov_b64 s[38:39], 0
